# D2: nt hint also on the bf16 out-proj result loads (read once)
# baseline (speedup 1.0000x reference)
; template <int NR>
; DI void resid_rows(const Params& p, int l, int row0, const float* xin) {
;     ...
;   u32x2 ob[NR][4]; f32x4 xv[NR][4]; f32x4 sq[NR][2];
; #pragma unroll
;   for (int r = 0; r < NR; ++r) {
;     const size_t row = (size_t)(row0 + r);
;     sq[r][0] = *(const f32x4*)(ssq + row * 16); sq[r][1] = *(const f32x4*)(ssq + row * 16 + 4);
; #pragma unroll
;     for (int i = 0; i < 4; ++i) { const int idx = i * 256 + lane * 4; ob[r][i] = *(const u32x2*)(outb + row * 1024 + idx); xv[r][i] = *(const f32x4*)(xin + row * 1024 + idx); }
;   }
;   f32x4 gq[4];
.LBB0_592:
	s_mov_b64 s[6:7], 0
	s_add_u32 s8, s90, s6
	s_addc_u32 s9, s91, s7
	s_add_u32 s6, s8, 0xd4f0000
	v_mov_b32_e32 v0, v176
	s_addc_u32 s7, s9, 0
	s_add_u32 s10, s8, 0xb250000
	v_ashrrev_i32_e32 v105, 31, v104
	v_and_b32_e32 v149, 63, v0
	s_addc_u32 s11, s9, 0
	s_waitcnt lgkmcnt(0)
	v_lshlrev_b64 v[0:1], 6, v[104:105]
	v_lshl_add_u64 v[0:1], s[10:11], 0, v[0:1]
	v_lshlrev_b64 v[146:147], 11, v[104:105]
	v_lshlrev_b64 v[154:155], 12, v[104:105]
	global_load_dwordx4 v[100:103], v[0:1], off
	global_load_dwordx4 v[142:145], v[0:1], off offset:16
	v_lshl_add_u64 v[0:1], s[6:7], 0, v[146:147]
	v_lshl_add_u64 v[2:3], s[0:1], 0, v[154:155]
	v_lshlrev_b32_e32 v178, 3, v149
	v_lshlrev_b32_e32 v156, 4, v149
	v_mov_b32_e32 v157, v179
	v_add_u32_e32 v124, 1, v104
	v_lshl_add_u64 v[0:1], v[0:1], 0, v[178:179]
	v_lshl_add_u64 v[2:3], v[2:3], 0, v[156:157]
	v_ashrrev_i32_e32 v125, 31, v124
	global_load_dwordx4 v[150:153], v[2:3], off nt
	global_load_dwordx4 v[96:99], v[2:3], off offset:1024 nt
	global_load_dwordx2 v[158:159], v[0:1], off nt
	global_load_dwordx2 v[140:141], v[0:1], off offset:512 nt
	global_load_dwordx2 v[138:139], v[0:1], off offset:1024 nt
	global_load_dwordx2 v[136:137], v[0:1], off offset:1536 nt
	global_load_dwordx4 v[92:95], v[2:3], off offset:2048 nt
	global_load_dwordx4 v[88:91], v[2:3], off offset:3072 nt
	v_lshlrev_b64 v[0:1], 6, v[124:125]
	v_lshl_add_u64 v[0:1], s[10:11], 0, v[0:1]
	global_load_dwordx4 v[80:83], v[0:1], off offset:16
	global_load_dwordx4 v[84:87], v[0:1], off
	v_lshlrev_b64 v[0:1], 11, v[124:125]
	v_lshlrev_b64 v[2:3], 12, v[124:125]
	v_lshl_add_u64 v[0:1], s[6:7], 0, v[0:1]
	v_lshl_add_u64 v[2:3], s[0:1], 0, v[2:3]
	v_add_u32_e32 v114, 2, v104
	v_lshl_add_u64 v[0:1], v[0:1], 0, v[178:179]
	v_lshl_add_u64 v[2:3], v[2:3], 0, v[156:157]
	v_ashrrev_i32_e32 v115, 31, v114
	global_load_dwordx4 v[76:79], v[2:3], off nt
	global_load_dwordx4 v[72:75], v[2:3], off offset:1024 nt
	global_load_dwordx2 v[134:135], v[0:1], off nt
	global_load_dwordx2 v[132:133], v[0:1], off offset:512 nt
	global_load_dwordx2 v[130:131], v[0:1], off offset:1024 nt
	global_load_dwordx2 v[128:129], v[0:1], off offset:1536 nt
	global_load_dwordx4 v[68:71], v[2:3], off offset:2048 nt
	global_load_dwordx4 v[64:67], v[2:3], off offset:3072 nt
	v_lshlrev_b64 v[0:1], 6, v[114:115]
	v_lshl_add_u64 v[0:1], s[10:11], 0, v[0:1]
	v_lshlrev_b64 v[2:3], 12, v[114:115]
	global_load_dwordx4 v[56:59], v[0:1], off offset:16
	global_load_dwordx4 v[60:63], v[0:1], off
	v_lshlrev_b64 v[0:1], 11, v[114:115]
	v_lshl_add_u64 v[2:3], s[0:1], 0, v[2:3]
	v_lshl_add_u64 v[0:1], s[6:7], 0, v[0:1]
	v_lshl_add_u64 v[2:3], v[2:3], 0, v[156:157]
	v_lshl_add_u64 v[0:1], v[0:1], 0, v[178:179]
	global_load_dwordx4 v[52:55], v[2:3], off nt
	global_load_dwordx4 v[48:51], v[2:3], off offset:1024 nt
	global_load_dwordx2 v[126:127], v[0:1], off nt
	global_load_dwordx2 v[122:123], v[0:1], off offset:512 nt
	global_load_dwordx2 v[120:121], v[0:1], off offset:1024 nt
	global_load_dwordx2 v[118:119], v[0:1], off offset:1536 nt
	global_load_dwordx4 v[44:47], v[2:3], off offset:2048 nt
	global_load_dwordx4 v[40:43], v[2:3], off offset:3072 nt
	v_add_u32_e32 v106, 3, v104
	v_ashrrev_i32_e32 v107, 31, v106
	v_lshlrev_b64 v[0:1], 6, v[106:107]
	v_lshl_add_u64 v[0:1], s[10:11], 0, v[0:1]
	global_load_dwordx4 v[32:35], v[0:1], off offset:16
	global_load_dwordx4 v[36:39], v[0:1], off
	v_lshlrev_b64 v[0:1], 11, v[106:107]
	v_lshlrev_b64 v[2:3], 12, v[106:107]
	v_lshl_add_u64 v[0:1], s[6:7], 0, v[0:1]
	v_lshl_add_u64 v[2:3], s[0:1], 0, v[2:3]
	v_lshl_add_u64 v[0:1], v[0:1], 0, v[178:179]
	v_lshl_add_u64 v[2:3], v[2:3], 0, v[156:157]
	global_load_dwordx4 v[24:27], v156, s[2:3]
	global_load_dwordx4 v[28:31], v[2:3], off nt
	global_load_dwordx4 v[16:19], v[2:3], off offset:1024 nt
	global_load_dwordx2 v[116:117], v[0:1], off nt
	global_load_dwordx2 v[112:113], v[0:1], off offset:512 nt
	global_load_dwordx2 v[110:111], v[0:1], off offset:1024 nt
	global_load_dwordx2 v[108:109], v[0:1], off offset:1536 nt
	global_load_dwordx4 v[8:11], v[2:3], off offset:2048 nt
	s_nop 0
	global_load_dwordx4 v[0:3], v[2:3], off offset:3072 nt
	s_nop 0
	global_load_dwordx4 v[20:23], v156, s[2:3] offset:1024
	global_load_dwordx4 v[12:15], v156, s[2:3] offset:2048
	global_load_dwordx4 v[4:7], v156, s[2:3] offset:3072
	s_add_u32 s6, s8, 0x2a40000
	s_addc_u32 s7, s9, 0
	v_lshlrev_b32_e32 v148, 2, v149
	s_waitcnt vmcnt(43)
	v_mov_b32_e32 v160, v100
	s_waitcnt vmcnt(42)
	v_mov_b32_e32 v161, v142
	v_mov_b32_e32 v142, v101
	v_pk_add_f32 v[100:101], v[160:161], v[142:143]
	v_mov_b32_e32 v142, v102
	v_mov_b32_e32 v143, v144
	v_mov_b32_e32 v144, v103
	v_pk_add_f32 v[102:103], v[142:143], v[144:145]
	v_lshl_add_u64 v[142:143], s[6:7], 0, v[146:147]
	v_pk_add_f32 v[100:101], v[100:101], v[102:103]
	s_waitcnt vmcnt(39)
	v_lshlrev_b32_e32 v102, 16, v159
	v_add_f32_e32 v100, v100, v101
	v_fmamk_f32 v100, v100, 0x3a800000, v192
	v_mul_f32_e32 v101, 0x4b800000, v100
	v_cmp_gt_f32_e32 vcc, s92, v100
	v_and_b32_e32 v103, 0xffff0000, v159
	v_lshl_add_u64 v[146:147], s[88:89], 0, v[154:155]
	v_cndmask_b32_e32 v100, v100, v101, vcc
	v_rsq_f32_e32 v100, v100
	v_lshl_add_u64 v[146:147], v[146:147], 0, v[156:157]
	v_mul_f32_e32 v101, 0x45800000, v100
	v_cndmask_b32_e32 v144, v100, v101, vcc
	v_lshlrev_b32_e32 v100, 16, v158
	v_and_b32_e32 v101, 0xffff0000, v158
	v_pk_mul_f32 v[100:101], v[144:145], v[100:101] op_sel_hi:[0,1]
	v_pk_mul_f32 v[102:103], v[144:145], v[102:103] op_sel_hi:[0,1]
	v_cndmask_b32_e64 v145, 0, 1, s[4:5]
	v_cmp_ne_u32_e64 s[36:37], 1, v145
	s_andn2_b64 vcc, exec, s[4:5]
	s_waitcnt vmcnt(11)
	v_pk_fma_f32 v[100:101], v[100:101], v[24:25], v[150:151]
	v_pk_fma_f32 v[102:103], v[102:103], v[26:27], v[152:153]
	global_store_dwordx4 v[146:147], v[100:103], off nt
	s_cbranch_vccnz .LBB0_594
	v_lshlrev_b32_e32 v178, 1, v148
	v_cvt_pk_bf16_f32 v150, v100, v101
	v_cvt_pk_bf16_f32 v151, v102, v103
	v_lshl_add_u64 v[152:153], v[142:143], 0, v[178:179]
	global_store_dwordx2 v[152:153], v[150:151], off
